# vp56 plus P8 K-loop: the no-op s_setprio 0/1 pair in the middle of each 32-MFMA block removed (bytes kept as nops in the load segment)
# baseline (speedup 1.0000x reference)
; template <class Epi, class Sched, bool ALIGN_EPI = false, bool SP2 = false, bool FP8 = false, bool MIX8 = false>
; __device__ __forceinline__ void gemm_phase(PG8_LAS unsigned char* lds, const Gemm g, const Sched& S, const Epi& E) {
;     ...
;             const bool last = (t == nt - 2);
;             if constexpr (Epi::MID_HOOK) { if (t == E.mid_t(nt)) { if constexpr (FP8) asm volatile("s_nop 15\n\ts_nop 15\n\ts_nop 15" ::: "memory");
;                 E.mid(acc, cur, wr, wc, fr, fq); } }
;             const char* a1 = cA + (size_t)(t + 1) * kstep;
;             const char* a2 = last ? nA : cA + (size_t)(t + 2) * kstep; const char* b2 = last ? nB : cB + (size_t)(t + 2) * kstep;
;             const char* a3 = a2 + kstep; const char* b3 = b2 + kstep;
.LBB0_723:
	ds_read_b128 v[154:157], v149
	ds_read_b128 v[158:161], v149 offset:1024
	ds_read_b128 v[162:165], v149 offset:2048
	ds_read_b128 v[166:169], v149 offset:3072
	ds_read_b128 v[170:173], v150
	ds_read_b128 v[174:177], v150 offset:1024
	ds_read_b128 v[178:181], v150 offset:2048
	ds_read_b128 v[182:185], v150 offset:3072
	s_add_u32 s30, s28, 0xfff80080
	s_addc_u32 s31, s29, -1
	s_cmp_eq_u32 s59, 28
	s_cselect_b32 s35, s1, s31
	s_cselect_b32 s34, s9, s30
	s_cselect_b32 s31, s19, s33
	s_cselect_b32 s30, s21, s27
	v_lshl_add_u64 v[144:145], s[28:29], 0, v[136:137]
	s_add_i32 m0, s47, 0xc000
	ds_read_b128 v[186:189], v151
	ds_read_b128 v[190:193], v151 offset:1024
	ds_read_b128 v[194:197], v151 offset:2048
	ds_read_b128 v[198:201], v151 offset:3072
	ds_read_b128 v[202:205], v151 offset:4096
	ds_read_b128 v[206:209], v151 offset:5120
	ds_read_b128 v[210:213], v151 offset:6144
	ds_read_b128 v[214:217], v151 offset:7168
	global_load_lds_dwordx4 v[144:145], off
	v_lshl_add_u64 v[144:145], s[28:29], 0, v[138:139]
	s_add_i32 m0, s47, 0xe000
	s_nop 0
	global_load_lds_dwordx4 v[144:145], off
	s_nop 0
	s_nop 0
	s_waitcnt vmcnt(8)
	s_waitcnt lgkmcnt(0)
	s_barrier
	s_setprio 1
	s_waitcnt lgkmcnt(0)
	v_mfma_f32_16x16x32_bf16 v[124:127], v[154:157], v[186:189], v[124:127]
	v_mfma_f32_16x16x32_bf16 v[120:123], v[162:165], v[186:189], v[120:123]
	v_mfma_f32_16x16x32_bf16 v[108:111], v[154:157], v[194:197], v[108:111]
	v_mfma_f32_16x16x32_bf16 v[104:107], v[162:165], v[194:197], v[104:107]
	v_mfma_f32_16x16x32_bf16 v[92:95], v[154:157], v[202:205], v[92:95]
	v_mfma_f32_16x16x32_bf16 v[88:91], v[162:165], v[202:205], v[88:91]
	v_mfma_f32_16x16x32_bf16 v[76:79], v[154:157], v[210:213], v[76:79]
	v_mfma_f32_16x16x32_bf16 v[72:75], v[162:165], v[210:213], v[72:75]
	v_mfma_f32_16x16x32_bf16 v[124:127], v[158:161], v[190:193], v[124:127]
	v_mfma_f32_16x16x32_bf16 v[120:123], v[166:169], v[190:193], v[120:123]
	v_mfma_f32_16x16x32_bf16 v[108:111], v[158:161], v[198:201], v[108:111]
	v_mfma_f32_16x16x32_bf16 v[104:107], v[166:169], v[198:201], v[104:107]
	v_mfma_f32_16x16x32_bf16 v[92:95], v[158:161], v[206:209], v[92:95]
	v_mfma_f32_16x16x32_bf16 v[88:91], v[166:169], v[206:209], v[88:91]
	v_mfma_f32_16x16x32_bf16 v[76:79], v[158:161], v[214:217], v[76:79]
	v_mfma_f32_16x16x32_bf16 v[72:75], v[166:169], v[214:217], v[72:75]
	v_mfma_f32_16x16x32_bf16 v[116:119], v[170:173], v[186:189], v[116:119]
	v_mfma_f32_16x16x32_bf16 v[112:115], v[178:181], v[186:189], v[112:115]
	v_mfma_f32_16x16x32_bf16 v[100:103], v[170:173], v[194:197], v[100:103]
	v_mfma_f32_16x16x32_bf16 v[96:99], v[178:181], v[194:197], v[96:99]
	v_mfma_f32_16x16x32_bf16 v[84:87], v[170:173], v[202:205], v[84:87]
	v_mfma_f32_16x16x32_bf16 v[80:83], v[178:181], v[202:205], v[80:83]
	v_mfma_f32_16x16x32_bf16 v[68:71], v[170:173], v[210:213], v[68:71]
	v_mfma_f32_16x16x32_bf16 v[64:67], v[178:181], v[210:213], v[64:67]
	v_mfma_f32_16x16x32_bf16 v[116:119], v[174:177], v[190:193], v[116:119]
	v_mfma_f32_16x16x32_bf16 v[112:115], v[182:185], v[190:193], v[112:115]
	v_mfma_f32_16x16x32_bf16 v[100:103], v[174:177], v[198:201], v[100:103]
	v_mfma_f32_16x16x32_bf16 v[96:99], v[182:185], v[198:201], v[96:99]
	v_mfma_f32_16x16x32_bf16 v[84:87], v[174:177], v[206:209], v[84:87]
	v_mfma_f32_16x16x32_bf16 v[80:83], v[182:185], v[206:209], v[80:83]
	v_mfma_f32_16x16x32_bf16 v[68:71], v[174:177], v[214:217], v[68:71]
	v_mfma_f32_16x16x32_bf16 v[64:67], v[182:185], v[214:217], v[64:67]
	s_setprio 0
	s_barrier
	s_add_i32 s60, s56, s46
	v_lshl_add_u64 v[144:145], s[30:31], 0, v[130:131]
	s_mov_b32 m0, s60
	ds_read_b128 v[186:189], v151 offset:16384
	ds_read_b128 v[190:193], v151 offset:17408
	ds_read_b128 v[194:197], v151 offset:18432
	ds_read_b128 v[198:201], v151 offset:19456
	ds_read_b128 v[202:205], v151 offset:20480
	ds_read_b128 v[206:209], v151 offset:21504
	ds_read_b128 v[210:213], v151 offset:22528
	ds_read_b128 v[214:217], v151 offset:23552
	global_load_lds_dwordx4 v[144:145], off
	s_add_i32 m0, s60, 0x2000
	s_add_u32 s60, s30, 0x80000
	v_lshl_add_u64 v[218:219], s[30:31], 0, v[134:135]
	s_addc_u32 s61, s31, 0
	s_add_i32 s62, s57, s46
	global_load_lds_dwordx4 v[218:219], off
	v_lshl_add_u64 v[220:221], s[60:61], 0, v[130:131]
	s_mov_b32 m0, s62
	v_lshl_add_u64 v[222:223], s[34:35], 0, v[132:133]
	global_load_lds_dwordx4 v[220:221], off
	v_lshl_add_u64 v[220:221], s[60:61], 0, v[134:135]
	s_add_i32 m0, s62, 0x2000
	s_nop 0
	global_load_lds_dwordx4 v[220:221], off
	v_lshl_add_u64 v[220:221], s[34:35], 0, v[128:129]
	s_mov_b32 m0, s47
	s_nop 0
	global_load_lds_dwordx4 v[220:221], off
	s_mov_b32 m0, s36
	s_nop 0
	global_load_lds_dwordx4 v[222:223], off
	s_nop 0
	s_nop 0
	s_waitcnt vmcnt(8)
	s_waitcnt lgkmcnt(0)
	s_barrier
	s_setprio 1
	s_waitcnt lgkmcnt(0)
	v_mfma_f32_16x16x32_bf16 v[60:63], v[154:157], v[186:189], v[60:63]
	v_mfma_f32_16x16x32_bf16 v[56:59], v[162:165], v[186:189], v[56:59]
	v_mfma_f32_16x16x32_bf16 v[44:47], v[154:157], v[194:197], v[44:47]
	v_mfma_f32_16x16x32_bf16 v[40:43], v[162:165], v[194:197], v[40:43]
	v_mfma_f32_16x16x32_bf16 v[28:31], v[154:157], v[202:205], v[28:31]
	v_mfma_f32_16x16x32_bf16 v[24:27], v[162:165], v[202:205], v[24:27]
	v_mfma_f32_16x16x32_bf16 v[12:15], v[154:157], v[210:213], v[12:15]
	v_mfma_f32_16x16x32_bf16 v[8:11], v[162:165], v[210:213], v[8:11]
	v_mfma_f32_16x16x32_bf16 v[60:63], v[158:161], v[190:193], v[60:63]
	v_mfma_f32_16x16x32_bf16 v[56:59], v[166:169], v[190:193], v[56:59]
	v_mfma_f32_16x16x32_bf16 v[44:47], v[158:161], v[198:201], v[44:47]
	v_mfma_f32_16x16x32_bf16 v[40:43], v[166:169], v[198:201], v[40:43]
	v_mfma_f32_16x16x32_bf16 v[28:31], v[158:161], v[206:209], v[28:31]
	v_mfma_f32_16x16x32_bf16 v[24:27], v[166:169], v[206:209], v[24:27]
	v_mfma_f32_16x16x32_bf16 v[12:15], v[158:161], v[214:217], v[12:15]
	v_mfma_f32_16x16x32_bf16 v[8:11], v[166:169], v[214:217], v[8:11]
	v_mfma_f32_16x16x32_bf16 v[52:55], v[170:173], v[186:189], v[52:55]
	v_mfma_f32_16x16x32_bf16 v[48:51], v[178:181], v[186:189], v[48:51]
	v_mfma_f32_16x16x32_bf16 v[36:39], v[170:173], v[194:197], v[36:39]
	v_mfma_f32_16x16x32_bf16 v[32:35], v[178:181], v[194:197], v[32:35]
	v_mfma_f32_16x16x32_bf16 v[20:23], v[170:173], v[202:205], v[20:23]
	v_mfma_f32_16x16x32_bf16 v[16:19], v[178:181], v[202:205], v[16:19]
	v_mfma_f32_16x16x32_bf16 v[4:7], v[170:173], v[210:213], v[4:7]
	v_mfma_f32_16x16x32_bf16 v[0:3], v[178:181], v[210:213], v[0:3]
	v_mfma_f32_16x16x32_bf16 v[52:55], v[174:177], v[190:193], v[52:55]
	v_mfma_f32_16x16x32_bf16 v[48:51], v[182:185], v[190:193], v[48:51]
	v_mfma_f32_16x16x32_bf16 v[36:39], v[174:177], v[198:201], v[36:39]
	v_mfma_f32_16x16x32_bf16 v[32:35], v[182:185], v[198:201], v[32:35]
	v_mfma_f32_16x16x32_bf16 v[20:23], v[174:177], v[206:209], v[20:23]
	v_mfma_f32_16x16x32_bf16 v[16:19], v[182:185], v[206:209], v[16:19]
	v_mfma_f32_16x16x32_bf16 v[4:7], v[174:177], v[214:217], v[4:7]
	v_mfma_f32_16x16x32_bf16 v[0:3], v[182:185], v[214:217], v[0:3]
	s_setprio 0
	s_barrier
	s_add_i32 s60, 0, 0x18000
	v_add_u32_e32 v153, s60, v147
	s_add_i32 s61, 0, 0x1c000
	ds_read_b128 v[154:157], v153
	ds_read_b128 v[158:161], v153 offset:1024
	ds_read_b128 v[162:165], v153 offset:2048
	ds_read_b128 v[166:169], v153 offset:3072
	v_add_u32_e32 v153, s61, v147
	ds_read_b128 v[170:173], v153
	ds_read_b128 v[174:177], v153 offset:1024
	ds_read_b128 v[178:181], v153 offset:2048
	ds_read_b128 v[182:185], v153 offset:3072
	s_add_u32 s34, s34, 0x80000
	s_addc_u32 s35, s35, 0
	s_mov_b32 m0, s37
	v_lshl_add_u64 v[224:225], s[34:35], 0, v[128:129]
	ds_read_b128 v[186:189], v151 offset:32768
	ds_read_b128 v[190:193], v151 offset:33792
	ds_read_b128 v[194:197], v151 offset:34816
	ds_read_b128 v[198:201], v151 offset:35840
	ds_read_b128 v[202:205], v151 offset:36864
	ds_read_b128 v[206:209], v151 offset:37888
	ds_read_b128 v[210:213], v151 offset:38912
	ds_read_b128 v[214:217], v151 offset:39936
	global_load_lds_dwordx4 v[224:225], off
	v_lshl_add_u64 v[224:225], s[34:35], 0, v[132:133]
	s_mov_b32 m0, s48
	s_nop 0
	global_load_lds_dwordx4 v[224:225], off
	s_nop 0
	s_nop 0
	s_waitcnt vmcnt(8)
	s_waitcnt lgkmcnt(0)
	s_barrier
	s_setprio 1
	s_waitcnt lgkmcnt(0)
	v_mfma_f32_16x16x32_bf16 v[124:127], v[154:157], v[186:189], v[124:127]
	v_mfma_f32_16x16x32_bf16 v[120:123], v[162:165], v[186:189], v[120:123]
	v_mfma_f32_16x16x32_bf16 v[108:111], v[154:157], v[194:197], v[108:111]
	v_mfma_f32_16x16x32_bf16 v[104:107], v[162:165], v[194:197], v[104:107]
	v_mfma_f32_16x16x32_bf16 v[92:95], v[154:157], v[202:205], v[92:95]
	v_mfma_f32_16x16x32_bf16 v[88:91], v[162:165], v[202:205], v[88:91]
	v_mfma_f32_16x16x32_bf16 v[76:79], v[154:157], v[210:213], v[76:79]
	v_mfma_f32_16x16x32_bf16 v[72:75], v[162:165], v[210:213], v[72:75]
	v_mfma_f32_16x16x32_bf16 v[124:127], v[158:161], v[190:193], v[124:127]
	v_mfma_f32_16x16x32_bf16 v[120:123], v[166:169], v[190:193], v[120:123]
	v_mfma_f32_16x16x32_bf16 v[108:111], v[158:161], v[198:201], v[108:111]
	v_mfma_f32_16x16x32_bf16 v[104:107], v[166:169], v[198:201], v[104:107]
	v_mfma_f32_16x16x32_bf16 v[92:95], v[158:161], v[206:209], v[92:95]
	v_mfma_f32_16x16x32_bf16 v[88:91], v[166:169], v[206:209], v[88:91]
	v_mfma_f32_16x16x32_bf16 v[76:79], v[158:161], v[214:217], v[76:79]
	v_mfma_f32_16x16x32_bf16 v[72:75], v[166:169], v[214:217], v[72:75]
	v_mfma_f32_16x16x32_bf16 v[116:119], v[170:173], v[186:189], v[116:119]
	v_mfma_f32_16x16x32_bf16 v[112:115], v[178:181], v[186:189], v[112:115]
	v_mfma_f32_16x16x32_bf16 v[100:103], v[170:173], v[194:197], v[100:103]
	v_mfma_f32_16x16x32_bf16 v[96:99], v[178:181], v[194:197], v[96:99]
	v_mfma_f32_16x16x32_bf16 v[84:87], v[170:173], v[202:205], v[84:87]
	v_mfma_f32_16x16x32_bf16 v[80:83], v[178:181], v[202:205], v[80:83]
	v_mfma_f32_16x16x32_bf16 v[68:71], v[170:173], v[210:213], v[68:71]
	v_mfma_f32_16x16x32_bf16 v[64:67], v[178:181], v[210:213], v[64:67]
	v_mfma_f32_16x16x32_bf16 v[116:119], v[174:177], v[190:193], v[116:119]
	v_mfma_f32_16x16x32_bf16 v[112:115], v[182:185], v[190:193], v[112:115]
	v_mfma_f32_16x16x32_bf16 v[100:103], v[174:177], v[198:201], v[100:103]
	v_mfma_f32_16x16x32_bf16 v[96:99], v[182:185], v[198:201], v[96:99]
	v_mfma_f32_16x16x32_bf16 v[84:87], v[174:177], v[206:209], v[84:87]
	v_mfma_f32_16x16x32_bf16 v[80:83], v[182:185], v[206:209], v[80:83]
	v_mfma_f32_16x16x32_bf16 v[68:71], v[174:177], v[214:217], v[68:71]
	v_mfma_f32_16x16x32_bf16 v[64:67], v[182:185], v[214:217], v[64:67]
	s_setprio 0
	s_barrier
; #define PG8_BAR __builtin_amdgcn_s_barrier()
; template <class Epi, class Sched, bool ALIGN_EPI = false, bool SP2 = false, bool FP8 = false, bool MIX8 = false>
; __device__ __forceinline__ void gemm_phase(PG8_LAS unsigned char* lds, const Gemm g, const Sched& S, const Epi& E) {
;     ...
;         if constexpr (ALIGN_EPI) { if (wr == 0) PG8_BAR; }
	s_add_i32 s34, s60, s46
	v_lshl_add_u64 v[144:145], v[144:145], 0, s[14:15]
	s_mov_b32 m0, s34
	ds_read_b128 v[186:189], v151 offset:49152
	ds_read_b128 v[190:193], v151 offset:50176
	ds_read_b128 v[194:197], v151 offset:51200
	ds_read_b128 v[198:201], v151 offset:52224
	ds_read_b128 v[202:205], v151 offset:53248
	ds_read_b128 v[206:209], v151 offset:54272
	ds_read_b128 v[210:213], v151 offset:55296
	ds_read_b128 v[214:217], v151 offset:56320
	global_load_lds_dwordx4 v[144:145], off
	s_add_i32 m0, s34, 0x2000
	s_add_u32 s30, s30, 0x80080
	v_lshl_add_u64 v[144:145], v[218:219], 0, s[14:15]
	s_addc_u32 s31, s31, 0
	s_add_i32 s34, s61, s46
	global_load_lds_dwordx4 v[144:145], off
	v_lshl_add_u64 v[144:145], s[30:31], 0, v[130:131]
	s_mov_b32 m0, s34
	s_nop 0
	global_load_lds_dwordx4 v[144:145], off
	v_lshl_add_u64 v[144:145], s[30:31], 0, v[134:135]
	s_add_i32 m0, s34, 0x2000
	s_nop 0
	global_load_lds_dwordx4 v[144:145], off
	v_lshl_add_u64 v[144:145], v[220:221], 0, s[14:15]
	s_mov_b32 m0, s50
	s_nop 0
	global_load_lds_dwordx4 v[144:145], off
	v_lshl_add_u64 v[144:145], v[222:223], 0, s[14:15]
	s_mov_b32 m0, s51
	s_nop 0
	global_load_lds_dwordx4 v[144:145], off
	s_nop 0
	s_nop 0
	s_waitcnt vmcnt(8)
	s_waitcnt lgkmcnt(0)
	s_barrier
	s_setprio 1
	s_waitcnt lgkmcnt(0)
	v_mfma_f32_16x16x32_bf16 v[60:63], v[154:157], v[186:189], v[60:63]
	v_mfma_f32_16x16x32_bf16 v[56:59], v[162:165], v[186:189], v[56:59]
	v_mfma_f32_16x16x32_bf16 v[44:47], v[154:157], v[194:197], v[44:47]
	v_mfma_f32_16x16x32_bf16 v[40:43], v[162:165], v[194:197], v[40:43]
	v_mfma_f32_16x16x32_bf16 v[28:31], v[154:157], v[202:205], v[28:31]
	v_mfma_f32_16x16x32_bf16 v[24:27], v[162:165], v[202:205], v[24:27]
	v_mfma_f32_16x16x32_bf16 v[12:15], v[154:157], v[210:213], v[12:15]
	v_mfma_f32_16x16x32_bf16 v[8:11], v[162:165], v[210:213], v[8:11]
	v_mfma_f32_16x16x32_bf16 v[60:63], v[158:161], v[190:193], v[60:63]
	v_mfma_f32_16x16x32_bf16 v[56:59], v[166:169], v[190:193], v[56:59]
	v_mfma_f32_16x16x32_bf16 v[44:47], v[158:161], v[198:201], v[44:47]
	v_mfma_f32_16x16x32_bf16 v[40:43], v[166:169], v[198:201], v[40:43]
	v_mfma_f32_16x16x32_bf16 v[28:31], v[158:161], v[206:209], v[28:31]
	v_mfma_f32_16x16x32_bf16 v[24:27], v[166:169], v[206:209], v[24:27]
	v_mfma_f32_16x16x32_bf16 v[12:15], v[158:161], v[214:217], v[12:15]
	v_mfma_f32_16x16x32_bf16 v[8:11], v[166:169], v[214:217], v[8:11]
	v_mfma_f32_16x16x32_bf16 v[52:55], v[170:173], v[186:189], v[52:55]
	v_mfma_f32_16x16x32_bf16 v[48:51], v[178:181], v[186:189], v[48:51]
	v_mfma_f32_16x16x32_bf16 v[36:39], v[170:173], v[194:197], v[36:39]
	v_mfma_f32_16x16x32_bf16 v[32:35], v[178:181], v[194:197], v[32:35]
	v_mfma_f32_16x16x32_bf16 v[20:23], v[170:173], v[202:205], v[20:23]
	v_mfma_f32_16x16x32_bf16 v[16:19], v[178:181], v[202:205], v[16:19]
	v_mfma_f32_16x16x32_bf16 v[4:7], v[170:173], v[210:213], v[4:7]
	v_mfma_f32_16x16x32_bf16 v[0:3], v[178:181], v[210:213], v[0:3]
	v_mfma_f32_16x16x32_bf16 v[52:55], v[174:177], v[190:193], v[52:55]
	v_mfma_f32_16x16x32_bf16 v[48:51], v[182:185], v[190:193], v[48:51]
	v_mfma_f32_16x16x32_bf16 v[36:39], v[174:177], v[198:201], v[36:39]
	v_mfma_f32_16x16x32_bf16 v[32:35], v[182:185], v[198:201], v[32:35]
	v_mfma_f32_16x16x32_bf16 v[20:23], v[174:177], v[206:209], v[20:23]
	v_mfma_f32_16x16x32_bf16 v[16:19], v[182:185], v[206:209], v[16:19]
	v_mfma_f32_16x16x32_bf16 v[4:7], v[174:177], v[214:217], v[4:7]
	v_mfma_f32_16x16x32_bf16 v[0:3], v[182:185], v[214:217], v[0:3]
	s_setprio 0
	s_barrier
	s_add_i32 s59, s59, 2
	s_add_u32 s28, s28, 0x100
	s_addc_u32 s29, s29, 0
	s_add_u32 s27, s27, 0x100
	s_addc_u32 s33, s33, 0
	s_cmp_gt_u32 s59, 29
	s_cbranch_scc0 .LBB0_723
	s_and_b64 vcc, exec, s[16:17]
	s_cbranch_vccz .LBB0_726
	s_barrier
